# attention unit-2 loop keeps Q fragments in registers (4 fewer ds_read_b128 per tile), K fragment reads issued 2 MFMAs ahead; row-sum in MFMA gaps uses scalar adds
# speedup vs baseline: 1.0060x; 1.0060x over previous
.Lfar1_noresc:
	v_fmamk_f32 v189, v64, 0x3fb8aa3b, v192
	v_exp_f32_e32 v180, v189
	v_fmamk_f32 v189, v65, 0x3fb8aa3b, v192
	v_exp_f32_e32 v181, v189
	v_fmamk_f32 v189, v66, 0x3fb8aa3b, v192
	v_exp_f32_e32 v182, v189
	v_fmamk_f32 v189, v67, 0x3fb8aa3b, v192
	v_exp_f32_e32 v183, v189
	v_fmamk_f32 v189, v68, 0x3fb8aa3b, v192
	v_exp_f32_e32 v184, v189
	v_fmamk_f32 v189, v69, 0x3fb8aa3b, v192
	v_exp_f32_e32 v185, v189
	v_fmamk_f32 v189, v70, 0x3fb8aa3b, v192
	v_exp_f32_e32 v186, v189
	v_fmamk_f32 v189, v71, 0x3fb8aa3b, v192
	v_exp_f32_e32 v187, v189
	v_cvt_pk_bf16_f32 v64, v180, v181
	v_cvt_pk_bf16_f32 v65, v182, v183
	v_cvt_pk_bf16_f32 v66, v184, v185
	v_cvt_pk_bf16_f32 v67, v186, v187
	s_nop 1
	s_waitcnt lgkmcnt(6)
	v_mfma_f32_32x32x16_bf16 v[48:63], v[198:201], v[64:67], v[48:63]
	ds_read_b64_tr_b16 v[198:199], v210 offset:39936
	ds_read_b64_tr_b16 v[200:201], v210 offset:42496
	v_add_f32_e32 v196, v180, v182
	v_add_f32_e32 v197, v181, v183
	v_add_f32_e32 v196, v196, v184
	v_add_f32_e32 v197, v197, v185
	v_add_f32_e32 v196, v196, v186
	v_add_f32_e32 v197, v197, v187
	v_fmamk_f32 v189, v72, 0x3fb8aa3b, v192
	v_exp_f32_e32 v180, v189
	v_fmamk_f32 v189, v73, 0x3fb8aa3b, v192
	v_exp_f32_e32 v181, v189
	s_waitcnt lgkmcnt(6)
	v_mfma_f32_32x32x16_bf16 v[32:47], v[202:205], v[64:67], v[32:47]
	ds_read_b64_tr_b16 v[202:203], v210 offset:40000
	ds_read_b64_tr_b16 v[204:205], v210 offset:42560
	v_fmamk_f32 v189, v74, 0x3fb8aa3b, v192
	v_exp_f32_e32 v182, v189
	v_fmamk_f32 v189, v75, 0x3fb8aa3b, v192
	v_exp_f32_e32 v183, v189
	s_waitcnt lgkmcnt(6)
	v_mfma_f32_32x32x16_bf16 v[16:31], v[206:209], v[64:67], v[16:31]
	ds_read_b64_tr_b16 v[206:207], v210 offset:40064
	ds_read_b64_tr_b16 v[208:209], v210 offset:42624
	v_fmamk_f32 v189, v76, 0x3fb8aa3b, v192
	v_exp_f32_e32 v184, v189
	v_fmamk_f32 v189, v77, 0x3fb8aa3b, v192
	v_exp_f32_e32 v185, v189
	s_waitcnt lgkmcnt(6)
	v_mfma_f32_32x32x16_bf16 v[0:15], v[250:253], v[64:67], v[0:15]
	ds_read_b64_tr_b16 v[250:251], v210 offset:40128
	ds_read_b64_tr_b16 v[252:253], v210 offset:42688
	v_fmamk_f32 v189, v78, 0x3fb8aa3b, v192
	v_exp_f32_e32 v186, v189
	v_fmamk_f32 v189, v79, 0x3fb8aa3b, v192
	v_exp_f32_e32 v187, v189
	v_cvt_pk_bf16_f32 v72, v180, v181
	v_cvt_pk_bf16_f32 v73, v182, v183
	v_cvt_pk_bf16_f32 v74, v184, v185
	v_cvt_pk_bf16_f32 v75, v186, v187
	s_nop 1
	s_waitcnt lgkmcnt(6)
	v_mfma_f32_32x32x16_bf16 v[48:63], v[198:201], v[72:75], v[48:63]
	ds_read_b64_tr_b16 v[198:199], v210 offset:45056
	ds_read_b64_tr_b16 v[200:201], v210 offset:47616
	v_add_f32_e32 v196, v196, v180
	v_add_f32_e32 v197, v197, v181
	v_add_f32_e32 v196, v196, v182
	v_add_f32_e32 v197, v197, v183
	v_add_f32_e32 v196, v196, v184
	v_add_f32_e32 v197, v197, v185
	v_add_f32_e32 v196, v196, v186
	v_add_f32_e32 v197, v197, v187
	v_fmamk_f32 v189, v80, 0x3fb8aa3b, v192
	v_exp_f32_e32 v180, v189
	v_fmamk_f32 v189, v81, 0x3fb8aa3b, v192
	v_exp_f32_e32 v181, v189
	s_waitcnt lgkmcnt(6)
	v_mfma_f32_32x32x16_bf16 v[32:47], v[202:205], v[72:75], v[32:47]
	ds_read_b64_tr_b16 v[202:203], v210 offset:45120
	ds_read_b64_tr_b16 v[204:205], v210 offset:47680
	v_fmamk_f32 v189, v82, 0x3fb8aa3b, v192
	v_exp_f32_e32 v182, v189
	v_fmamk_f32 v189, v83, 0x3fb8aa3b, v192
	v_exp_f32_e32 v183, v189
	s_waitcnt lgkmcnt(6)
	v_mfma_f32_32x32x16_bf16 v[16:31], v[206:209], v[72:75], v[16:31]
	ds_read_b64_tr_b16 v[206:207], v210 offset:45184
	ds_read_b64_tr_b16 v[208:209], v210 offset:47744
	v_fmamk_f32 v189, v84, 0x3fb8aa3b, v192
	v_exp_f32_e32 v184, v189
	v_fmamk_f32 v189, v85, 0x3fb8aa3b, v192
	v_exp_f32_e32 v185, v189
	s_waitcnt lgkmcnt(6)
	v_mfma_f32_32x32x16_bf16 v[0:15], v[250:253], v[72:75], v[0:15]
	ds_read_b64_tr_b16 v[250:251], v210 offset:45248
	ds_read_b64_tr_b16 v[252:253], v210 offset:47808
	v_fmamk_f32 v189, v86, 0x3fb8aa3b, v192
	v_exp_f32_e32 v186, v189
	v_fmamk_f32 v189, v87, 0x3fb8aa3b, v192
	v_exp_f32_e32 v187, v189
	v_cvt_pk_bf16_f32 v80, v180, v181
	v_cvt_pk_bf16_f32 v81, v182, v183
	v_cvt_pk_bf16_f32 v82, v184, v185
	v_cvt_pk_bf16_f32 v83, v186, v187
	s_nop 1
	s_waitcnt lgkmcnt(6)
	v_mfma_f32_32x32x16_bf16 v[48:63], v[198:201], v[80:83], v[48:63]
	ds_read_b64_tr_b16 v[198:199], v210 offset:50176
	ds_read_b64_tr_b16 v[200:201], v210 offset:52736
	v_add_f32_e32 v196, v196, v180
	v_add_f32_e32 v197, v197, v181
	v_add_f32_e32 v196, v196, v182
	v_add_f32_e32 v197, v197, v183
	v_add_f32_e32 v196, v196, v184
	v_add_f32_e32 v197, v197, v185
	v_add_f32_e32 v196, v196, v186
	v_add_f32_e32 v197, v197, v187
	v_fmamk_f32 v189, v88, 0x3fb8aa3b, v192
	v_exp_f32_e32 v180, v189
	v_fmamk_f32 v189, v89, 0x3fb8aa3b, v192
	v_exp_f32_e32 v181, v189
	s_waitcnt lgkmcnt(6)
	v_mfma_f32_32x32x16_bf16 v[32:47], v[202:205], v[80:83], v[32:47]
	ds_read_b64_tr_b16 v[202:203], v210 offset:50240
	ds_read_b64_tr_b16 v[204:205], v210 offset:52800
	v_fmamk_f32 v189, v90, 0x3fb8aa3b, v192
	v_exp_f32_e32 v182, v189
	v_fmamk_f32 v189, v91, 0x3fb8aa3b, v192
	v_exp_f32_e32 v183, v189
	s_waitcnt lgkmcnt(6)
	v_mfma_f32_32x32x16_bf16 v[16:31], v[206:209], v[80:83], v[16:31]
	ds_read_b64_tr_b16 v[206:207], v210 offset:50304
	ds_read_b64_tr_b16 v[208:209], v210 offset:52864
	v_fmamk_f32 v189, v92, 0x3fb8aa3b, v192
	v_exp_f32_e32 v184, v189
	v_fmamk_f32 v189, v93, 0x3fb8aa3b, v192
	v_exp_f32_e32 v185, v189
	s_waitcnt lgkmcnt(6)
	v_mfma_f32_32x32x16_bf16 v[0:15], v[250:253], v[80:83], v[0:15]
	ds_read_b64_tr_b16 v[250:251], v210 offset:50368
	ds_read_b64_tr_b16 v[252:253], v210 offset:52928
	v_fmamk_f32 v189, v94, 0x3fb8aa3b, v192
	v_exp_f32_e32 v186, v189
	v_fmamk_f32 v189, v95, 0x3fb8aa3b, v192
	v_exp_f32_e32 v187, v189
	v_cvt_pk_bf16_f32 v88, v180, v181
	v_cvt_pk_bf16_f32 v89, v182, v183
	v_cvt_pk_bf16_f32 v90, v184, v185
	v_cvt_pk_bf16_f32 v91, v186, v187
	s_nop 1
	s_waitcnt lgkmcnt(6)
	v_mfma_f32_32x32x16_bf16 v[48:63], v[198:201], v[88:91], v[48:63]
	v_add_f32_e32 v196, v196, v180
	v_add_f32_e32 v197, v197, v181
	v_add_f32_e32 v196, v196, v182
	v_add_f32_e32 v197, v197, v183
	v_add_f32_e32 v196, v196, v184
	v_add_f32_e32 v197, v197, v185
	v_add_f32_e32 v196, v196, v186
	v_add_f32_e32 v197, v197, v187
	s_waitcnt lgkmcnt(4)
	v_mfma_f32_32x32x16_bf16 v[32:47], v[202:205], v[88:91], v[32:47]
	s_waitcnt lgkmcnt(2)
	v_mfma_f32_32x32x16_bf16 v[16:31], v[206:209], v[88:91], v[16:31]
	s_waitcnt lgkmcnt(0)
	v_mfma_f32_32x32x16_bf16 v[0:15], v[250:253], v[88:91], v[0:15]
	v_add_f32_e32 v82, v196, v197
	v_mov_b32_e32 v80, v194
	v_mov_b32_e32 v81, v191
	s_branch .Lattn1_tail

.LBB0_604:
	v_add_f32_e32 v80, 0, v80
	v_add_f32_e32 v80, v81, v80
	v_add_f32_e32 v80, v82, v80
	v_add_f32_e32 v80, v83, v80
	v_add_f32_e32 v80, v84, v80
	v_add_f32_e32 v80, v85, v80
	v_add_f32_e32 v80, v86, v80
	v_add_f32_e32 v80, v87, v80
	v_add_f32_e32 v80, v88, v80
	v_add_f32_e32 v80, v89, v80
	v_add_f32_e32 v80, v90, v80
	v_add_f32_e32 v80, v91, v80
	v_add_f32_e32 v80, v92, v80
	v_add_f32_e32 v80, v93, v80
	v_add_f32_e32 v80, v94, v80
	v_add_f32_e32 v80, v95, v80
	v_add_f32_e32 v80, v116, v80
	v_add_f32_e32 v80, v125, v80
	v_add_f32_e32 v80, v126, v80
	v_add_f32_e32 v80, v133, v80
	v_add_f32_e32 v80, v137, v80
	v_add_f32_e32 v80, v138, v80
	v_add_f32_e32 v80, v139, v80
	v_add_f32_e32 v80, v140, v80
	v_add_f32_e32 v80, v141, v80
	v_add_f32_e32 v80, v142, v80
	v_add_f32_e32 v80, v143, v80
	v_add_f32_e32 v80, v144, v80
	v_add_f32_e32 v80, v145, v80
	v_add_f32_e32 v80, v146, v80
	v_add_f32_e32 v80, v147, v80
	s_or_b32 s57, s33, s35
	v_add_f32_e32 v80, v149, v80
	v_or_b32_e32 v144, s57, v215
	v_add_f32_e32 v159, v148, v80
	s_addk_i32 s57, 0xff43
	v_mov_b32_e32 v143, v144
	v_add_u32_e32 v157, -9, v144
	v_add_u32_e32 v158, -8, v144
	v_add_u32_e32 v155, -11, v144
	v_add_u32_e32 v156, -10, v144
	v_add_u32_e32 v154, -16, v144
	v_subrev_u32_e32 v153, 17, v144
	v_subrev_u32_e32 v151, 19, v144
	v_subrev_u32_e32 v152, 18, v144
	v_subrev_u32_e32 v149, 25, v144
	v_subrev_u32_e32 v150, 24, v144
	v_subrev_u32_e32 v147, 27, v144
	v_subrev_u32_e32 v148, 26, v144
	v_subrev_u32_e32 v145, 41, v144
	v_subrev_u32_e32 v146, 40, v144
	v_subrev_u32_e32 v141, 43, v144
	v_subrev_u32_e32 v142, 42, v144
	v_subrev_u32_e32 v139, 49, v144
	v_subrev_u32_e32 v140, 48, v144
	v_subrev_u32_e32 v137, 51, v144
	v_subrev_u32_e32 v138, 50, v144
	v_subrev_u32_e32 v133, 57, v144
	v_subrev_u32_e32 v126, 56, v144
	v_subrev_u32_e32 v125, 59, v144
	v_subrev_u32_e32 v116, 58, v144
	s_sub_i32 s82, s33, 64
	v_add_u32_e32 v192, s33, v234
	s_mov_b32 s84, 1
	s_mov_b32 s86, 0
	s_mov_b32 s55, 0
	s_mov_b32 s54, 1
	ds_read_b128 v[204:207], v239
	ds_read_b128 v[208:211], v239 offset:32
	ds_read_b128 v[244:247], v239 offset:64
	ds_read_b128 v[248:251], v239 offset:96
	s_waitcnt lgkmcnt(0)

.LBB0_607:
	s_add_i32 s76, s86, 64
	s_bitcmp1_b32 s54, 0
	s_cselect_b32 s54, 0x4400, 0
	v_add_u32_e32 v176, s54, v229
	ds_read_b128 v[64:67], v176
	ds_read_b128 v[84:87], v176 offset:32
	ds_read_b128 v[88:91], v176 offset:64
	s_waitcnt lgkmcnt(2)
	v_mfma_f32_32x32x16_bf16 v[64:79], v[64:67], v[204:207], 0
	ds_read_b128 v[160:163], v176 offset:96
	s_waitcnt lgkmcnt(2)
	v_mfma_f32_32x32x16_bf16 v[64:79], v[84:87], v[208:211], v[64:79]
	ds_read_b128 v[164:167], v176 offset:8704
	s_waitcnt lgkmcnt(2)
	v_mfma_f32_32x32x16_bf16 v[64:79], v[88:91], v[244:247], v[64:79]
	ds_read_b128 v[168:171], v176 offset:8736
	s_waitcnt lgkmcnt(2)
	v_mfma_f32_32x32x16_bf16 v[64:79], v[160:163], v[248:251], v[64:79]
	ds_read_b128 v[172:175], v176 offset:8768
	s_waitcnt lgkmcnt(2)
	v_mfma_f32_32x32x16_bf16 v[80:95], v[164:167], v[204:207], 0
	ds_read_b128 v[160:163], v176 offset:8800
	s_waitcnt lgkmcnt(2)
	v_mfma_f32_32x32x16_bf16 v[80:95], v[168:171], v[208:211], v[80:95]
	s_waitcnt lgkmcnt(1)
	v_mfma_f32_32x32x16_bf16 v[80:95], v[172:175], v[244:247], v[80:95]
	s_waitcnt lgkmcnt(0)
	v_mfma_f32_32x32x16_bf16 v[80:95], v[160:163], v[248:251], v[80:95]
	s_cmp_ge_u32 s76, s57
	s_mov_b64 s[54:55], -1
	s_cbranch_scc0 .LBB0_609
	v_add_u32_e32 v160, s86, v120
	v_add_u32_e32 v186, 64, v160
	v_or_b32_e32 v162, 3, v186
	v_or_b32_e32 v163, 2, v186
	v_sub_u32_e32 v160, v144, v160
	v_sub_u32_e32 v185, v143, v186
	v_sub_u32_e32 v170, v143, v162
	v_sub_u32_e32 v171, v144, v163
	v_sub_u32_e32 v172, v157, v186
	v_sub_u32_e32 v173, v158, v186
	v_sub_u32_e32 v174, v155, v186
	v_sub_u32_e32 v175, v156, v186
	v_add_u32_e32 v184, 0xffffffa0, v160
	v_med3_i32 v160, v185, 0, v240
	v_med3_i32 v161, v192, 0, v240
	v_med3_i32 v162, v171, 0, v240
	v_med3_i32 v163, v170, 0, v240
	v_med3_i32 v164, v173, 0, v240
	v_med3_i32 v165, v172, 0, v240
	v_med3_i32 v166, v175, 0, v240
	v_med3_i32 v167, v174, 0, v240
	v_lshl_add_u32 v160, v160, 2, s49
	v_lshl_add_u32 v161, v161, 2, s49
	v_lshl_add_u32 v162, v162, 2, s49
	v_lshl_add_u32 v163, v163, 2, s49
	v_lshl_add_u32 v164, v164, 2, s49
	v_lshl_add_u32 v165, v165, 2, s49
	v_lshl_add_u32 v166, v166, 2, s49
	v_lshl_add_u32 v167, v167, 2, s49
	ds_read_b32 v160, v160
	ds_read_b32 v161, v161
	ds_read_b32 v162, v162
	ds_read_b32 v163, v163
	ds_read_b32 v164, v164
	ds_read_b32 v165, v165
	ds_read_b32 v166, v166
	ds_read_b32 v167, v167
	s_waitcnt lgkmcnt(6)
	v_pk_fma_f32 v[160:161], v[64:65], s[28:29], v[160:161] op_sel_hi:[1,0,1]
	v_cmp_lt_i32_e32 vcc, -1, v192
	s_waitcnt lgkmcnt(4)
	v_pk_fma_f32 v[162:163], v[66:67], s[28:29], v[162:163] op_sel_hi:[1,0,1]
	s_waitcnt lgkmcnt(2)
	v_pk_fma_f32 v[164:165], v[68:69], s[28:29], v[164:165] op_sel_hi:[1,0,1]
	v_cndmask_b32_e32 v169, v241, v161, vcc
	v_cmp_lt_i32_e32 vcc, -1, v185
	s_waitcnt lgkmcnt(0)
	v_pk_fma_f32 v[166:167], v[70:71], s[28:29], v[166:167] op_sel_hi:[1,0,1]
	v_sub_u32_e32 v179, v154, v186
	v_cndmask_b32_e32 v168, v241, v160, vcc
	v_cmp_lt_i32_e32 vcc, -1, v170
	v_pk_mul_f32 v[160:161], v[168:169], s[48:49] op_sel_hi:[1,0]
	v_max3_f32 v176, v168, s77, v169
	v_cndmask_b32_e32 v169, v241, v163, vcc
	v_cmp_lt_i32_e32 vcc, -1, v171
	v_sub_u32_e32 v180, v151, v186
	v_sub_u32_e32 v181, v152, v186
	v_cndmask_b32_e32 v168, v241, v162, vcc
	v_cmp_lt_i32_e32 vcc, -1, v172
	v_pk_mul_f32 v[162:163], v[168:169], s[48:49] op_sel_hi:[1,0]
	v_max3_f32 v170, v176, v168, v169
	v_cndmask_b32_e32 v169, v241, v165, vcc
	v_cmp_lt_i32_e32 vcc, -1, v173
	v_sub_u32_e32 v176, v153, v186
	v_sub_u32_e32 v182, v149, v186
	v_cndmask_b32_e32 v168, v241, v164, vcc
	v_cmp_lt_i32_e32 vcc, -1, v174
	v_pk_mul_f32 v[164:165], v[168:169], s[48:49] op_sel_hi:[1,0]
	v_max3_f32 v170, v170, v168, v169
	v_cndmask_b32_e32 v169, v241, v167, vcc
	v_cmp_lt_i32_e32 vcc, -1, v175
	v_sub_u32_e32 v183, v150, v186
	v_sub_u32_e32 v187, v147, v186
	v_cndmask_b32_e32 v168, v241, v166, vcc
	v_sub_u32_e32 v188, v148, v186
	v_pk_mul_f32 v[166:167], v[168:169], s[48:49] op_sel_hi:[1,0]
	v_max3_f32 v178, v170, v168, v169
	v_med3_i32 v168, v179, 0, v240
	v_med3_i32 v169, v176, 0, v240
	v_med3_i32 v170, v181, 0, v240
	v_med3_i32 v171, v180, 0, v240
	v_med3_i32 v172, v183, 0, v240
	v_med3_i32 v173, v182, 0, v240
	v_med3_i32 v174, v188, 0, v240
	v_med3_i32 v175, v187, 0, v240
	v_lshl_add_u32 v168, v168, 2, s49
	v_lshl_add_u32 v169, v169, 2, s49
	v_lshl_add_u32 v170, v170, 2, s49
	v_lshl_add_u32 v171, v171, 2, s49
	v_lshl_add_u32 v172, v172, 2, s49
	v_lshl_add_u32 v173, v173, 2, s49
	v_lshl_add_u32 v174, v174, 2, s49
	v_lshl_add_u32 v175, v175, 2, s49
	ds_read_b32 v168, v168
	ds_read_b32 v169, v169
	ds_read_b32 v170, v170
	ds_read_b32 v171, v171
	ds_read_b32 v172, v172
	ds_read_b32 v173, v173
	ds_read_b32 v174, v174
	ds_read_b32 v175, v175
	s_waitcnt lgkmcnt(6)
	v_pk_fma_f32 v[168:169], v[72:73], s[28:29], v[168:169] op_sel_hi:[1,0,1]
	v_cmp_lt_i32_e32 vcc, -1, v176
	s_waitcnt lgkmcnt(4)
	v_pk_fma_f32 v[170:171], v[74:75], s[28:29], v[170:171] op_sel_hi:[1,0,1]
	s_waitcnt lgkmcnt(2)
	v_pk_fma_f32 v[172:173], v[76:77], s[28:29], v[172:173] op_sel_hi:[1,0,1]
	v_cndmask_b32_e32 v177, v241, v169, vcc
	v_cmp_lt_i32_e32 vcc, -1, v179
	s_waitcnt lgkmcnt(0)
	v_pk_fma_f32 v[174:175], v[78:79], s[28:29], v[174:175] op_sel_hi:[1,0,1]
	v_or_b32_e32 v179, 34, v186
	v_cndmask_b32_e32 v176, v241, v168, vcc
	v_cmp_lt_i32_e32 vcc, -1, v180
	v_pk_mul_f32 v[168:169], v[176:177], s[48:49] op_sel_hi:[1,0]
	v_max3_f32 v178, v178, v176, v177
	v_cndmask_b32_e32 v177, v241, v171, vcc
	v_cmp_lt_i32_e32 vcc, -1, v181
	v_sub_u32_e32 v189, v144, v179
	v_sub_u32_e32 v190, v145, v186
	v_cndmask_b32_e32 v176, v241, v170, vcc
	v_cmp_lt_i32_e32 vcc, -1, v182
	v_pk_mul_f32 v[170:171], v[176:177], s[48:49] op_sel_hi:[1,0]
	v_max3_f32 v178, v178, v176, v177
	v_cndmask_b32_e32 v177, v241, v173, vcc
	v_cmp_lt_i32_e32 vcc, -1, v183
	v_sub_u32_e32 v191, v146, v186
	v_sub_u32_e32 v193, v141, v186
	v_cndmask_b32_e32 v176, v241, v172, vcc
	v_cmp_lt_i32_e32 vcc, -1, v187
	v_pk_mul_f32 v[172:173], v[176:177], s[48:49] op_sel_hi:[1,0]
	v_max3_f32 v178, v178, v176, v177
	v_cndmask_b32_e32 v177, v241, v175, vcc
	v_cmp_lt_i32_e32 vcc, -1, v188
	v_sub_u32_e32 v195, v142, v186
	v_med3_i32 v180, v191, 0, v240
	v_cndmask_b32_e32 v176, v241, v174, vcc
	v_pk_mul_f32 v[174:175], v[176:177], s[48:49] op_sel_hi:[1,0]
	v_max3_f32 v187, v178, v176, v177
	v_max_i32_e32 v177, 33, v185
	v_or_b32_e32 v178, 35, v186
	v_subrev_u32_e32 v177, 33, v177
	v_sub_u32_e32 v188, v143, v178
	v_med3_i32 v176, v184, 0, v240
	v_min_u32_e32 v177, 0x7f, v177
	v_med3_i32 v178, v189, 0, v240
	v_med3_i32 v179, v188, 0, v240
	v_med3_i32 v181, v190, 0, v240
	v_med3_i32 v182, v195, 0, v240
	v_med3_i32 v183, v193, 0, v240
	v_lshl_add_u32 v176, v176, 2, s49
	v_lshl_add_u32 v177, v177, 2, s49
	v_lshl_add_u32 v178, v178, 2, s49
	v_lshl_add_u32 v179, v179, 2, s49
	v_lshl_add_u32 v180, v180, 2, s49
	v_lshl_add_u32 v181, v181, 2, s49
	v_lshl_add_u32 v182, v182, 2, s49
	v_lshl_add_u32 v183, v183, 2, s49
	ds_read_b32 v176, v176
	ds_read_b32 v177, v177
	ds_read_b32 v178, v178
	ds_read_b32 v179, v179
	ds_read_b32 v180, v180
	ds_read_b32 v181, v181
	ds_read_b32 v182, v182
	ds_read_b32 v183, v183
	s_waitcnt lgkmcnt(6)
	v_pk_fma_f32 v[176:177], v[80:81], s[28:29], v[176:177] op_sel_hi:[1,0,1]
	v_cmp_lt_i32_e32 vcc, 32, v185
	s_waitcnt lgkmcnt(4)
	v_pk_fma_f32 v[178:179], v[82:83], s[28:29], v[178:179] op_sel_hi:[1,0,1]
	s_waitcnt lgkmcnt(2)
	v_pk_fma_f32 v[180:181], v[84:85], s[28:29], v[180:181] op_sel_hi:[1,0,1]
	v_cndmask_b32_e32 v185, v241, v177, vcc
	v_cmp_lt_i32_e32 vcc, -1, v184
	s_waitcnt lgkmcnt(0)
	v_pk_fma_f32 v[182:183], v[86:87], s[28:29], v[182:183] op_sel_hi:[1,0,1]
	v_sub_u32_e32 v196, v140, v186
	v_cndmask_b32_e32 v184, v241, v176, vcc
	v_cmp_lt_i32_e32 vcc, -1, v188
	v_pk_mul_f32 v[176:177], v[184:185], s[48:49] op_sel_hi:[1,0]
	v_max3_f32 v187, v187, v184, v185
	v_cndmask_b32_e32 v185, v241, v179, vcc
	v_cmp_lt_i32_e32 vcc, -1, v189
	v_sub_u32_e32 v198, v137, v186
	v_sub_u32_e32 v199, v138, v186
	v_cndmask_b32_e32 v184, v241, v178, vcc
	v_cmp_lt_i32_e32 vcc, -1, v190
	v_pk_mul_f32 v[178:179], v[184:185], s[48:49] op_sel_hi:[1,0]
	v_max3_f32 v187, v187, v184, v185
	v_cndmask_b32_e32 v185, v241, v181, vcc
	v_cmp_lt_i32_e32 vcc, -1, v191
	v_sub_u32_e32 v200, v133, v186
	v_sub_u32_e32 v201, v126, v186
	v_cndmask_b32_e32 v184, v241, v180, vcc
	v_cmp_lt_i32_e32 vcc, -1, v193
	v_pk_mul_f32 v[180:181], v[184:185], s[48:49] op_sel_hi:[1,0]
	v_max3_f32 v187, v187, v184, v185
	v_cndmask_b32_e32 v185, v241, v183, vcc
	v_cmp_lt_i32_e32 vcc, -1, v195
	v_sub_u32_e32 v195, v139, v186
	v_sub_u32_e32 v203, v116, v186
	v_cndmask_b32_e32 v184, v241, v182, vcc
	v_pk_mul_f32 v[182:183], v[184:185], s[48:49] op_sel_hi:[1,0]
	v_max3_f32 v193, v187, v184, v185
	v_med3_i32 v184, v196, 0, v240
	v_med3_i32 v185, v195, 0, v240
	v_med3_i32 v187, v199, 0, v240
	v_med3_i32 v188, v198, 0, v240
	v_med3_i32 v189, v201, 0, v240
	v_med3_i32 v190, v200, 0, v240
	v_sub_u32_e32 v202, v125, v186
	v_med3_i32 v186, v203, 0, v240
	v_lshl_add_u32 v184, v184, 2, s49
	v_lshl_add_u32 v185, v185, 2, s49
	v_lshl_add_u32 v187, v187, 2, s49
	v_lshl_add_u32 v188, v188, 2, s49
	v_lshl_add_u32 v189, v189, 2, s49
	v_lshl_add_u32 v190, v190, 2, s49
	v_lshl_add_u32 v191, v186, 2, s49
	v_med3_i32 v186, v202, 0, v240
	v_lshl_add_u32 v197, v186, 2, s49
	ds_read_b32 v184, v184
	ds_read_b32 v185, v185
	ds_read_b32 v186, v187
	ds_read_b32 v187, v188
	ds_read_b32 v188, v189
	ds_read_b32 v189, v190
	ds_read_b32 v190, v191
	ds_read_b32 v191, v197
	s_waitcnt lgkmcnt(6)
	v_pk_fma_f32 v[184:185], v[88:89], s[28:29], v[184:185] op_sel_hi:[1,0,1]
	v_cmp_lt_i32_e32 vcc, -1, v195
	s_waitcnt lgkmcnt(4)
	v_pk_fma_f32 v[186:187], v[90:91], s[28:29], v[186:187] op_sel_hi:[1,0,1]
	s_waitcnt lgkmcnt(2)
	v_pk_fma_f32 v[188:189], v[92:93], s[28:29], v[188:189] op_sel_hi:[1,0,1]
	v_cndmask_b32_e32 v197, v241, v185, vcc
	v_cmp_lt_i32_e32 vcc, -1, v196
	s_waitcnt lgkmcnt(0)
	v_pk_fma_f32 v[190:191], v[94:95], s[28:29], v[190:191] op_sel_hi:[1,0,1]
	s_mov_b64 s[54:55], 0
	v_cndmask_b32_e32 v196, v241, v184, vcc
	v_cmp_lt_i32_e32 vcc, -1, v198
	v_pk_mul_f32 v[184:185], v[196:197], s[48:49] op_sel_hi:[1,0]
	v_max3_f32 v193, v193, v196, v197
	v_cndmask_b32_e32 v197, v241, v187, vcc
	v_cmp_lt_i32_e32 vcc, -1, v199
	s_nop 1
	v_cndmask_b32_e32 v196, v241, v186, vcc
	v_cmp_lt_i32_e32 vcc, -1, v200
	v_pk_mul_f32 v[186:187], v[196:197], s[48:49] op_sel_hi:[1,0]
	v_max3_f32 v193, v193, v196, v197
	v_cndmask_b32_e32 v197, v241, v189, vcc
	v_cmp_lt_i32_e32 vcc, -1, v201
	s_nop 1
	v_cndmask_b32_e32 v196, v241, v188, vcc
	v_cmp_lt_i32_e32 vcc, -1, v202
	v_pk_mul_f32 v[188:189], v[196:197], s[48:49] op_sel_hi:[1,0]
	v_max3_f32 v193, v193, v196, v197
	v_cndmask_b32_e32 v197, v241, v191, vcc
	v_cmp_lt_i32_e32 vcc, -1, v203
	s_nop 1
	v_cndmask_b32_e32 v196, v241, v190, vcc
	v_pk_mul_f32 v[190:191], v[196:197], s[48:49] op_sel_hi:[1,0]
	v_max3_f32 v193, v193, v196, v197

.Lfar2_noresc:
	v_fmamk_f32 v169, v64, 0x3fb8aa3b, v172
	v_exp_f32_e32 v160, v169
	v_fmamk_f32 v169, v65, 0x3fb8aa3b, v172
	v_exp_f32_e32 v161, v169
	v_fmamk_f32 v169, v66, 0x3fb8aa3b, v172
	v_exp_f32_e32 v162, v169
	v_fmamk_f32 v169, v67, 0x3fb8aa3b, v172
	v_exp_f32_e32 v163, v169
	v_fmamk_f32 v169, v68, 0x3fb8aa3b, v172
	v_exp_f32_e32 v164, v169
	v_fmamk_f32 v169, v69, 0x3fb8aa3b, v172
	v_exp_f32_e32 v165, v169
	v_fmamk_f32 v169, v70, 0x3fb8aa3b, v172
	v_exp_f32_e32 v166, v169
	v_fmamk_f32 v169, v71, 0x3fb8aa3b, v172
	v_exp_f32_e32 v167, v169
	v_cvt_pk_bf16_f32 v64, v160, v161
	v_cvt_pk_bf16_f32 v65, v162, v163
	v_cvt_pk_bf16_f32 v66, v164, v165
	v_cvt_pk_bf16_f32 v67, v166, v167
	s_nop 1
	s_waitcnt lgkmcnt(6)
	v_mfma_f32_32x32x16_bf16 v[48:63], v[178:181], v[64:67], v[48:63]
	ds_read_b64_tr_b16 v[178:179], v177 offset:39936
	ds_read_b64_tr_b16 v[180:181], v177 offset:42496
	v_add_f32_e32 v190, v160, v162
	v_add_f32_e32 v191, v161, v163
	v_add_f32_e32 v190, v190, v164
	v_add_f32_e32 v191, v191, v165
	v_add_f32_e32 v190, v190, v166
	v_add_f32_e32 v191, v191, v167
	v_fmamk_f32 v169, v72, 0x3fb8aa3b, v172
	v_exp_f32_e32 v160, v169
	v_fmamk_f32 v169, v73, 0x3fb8aa3b, v172
	v_exp_f32_e32 v161, v169
	s_waitcnt lgkmcnt(6)
	v_mfma_f32_32x32x16_bf16 v[32:47], v[182:185], v[64:67], v[32:47]
	ds_read_b64_tr_b16 v[182:183], v177 offset:40000
	ds_read_b64_tr_b16 v[184:185], v177 offset:42560
	v_fmamk_f32 v169, v74, 0x3fb8aa3b, v172
	v_exp_f32_e32 v162, v169
	v_fmamk_f32 v169, v75, 0x3fb8aa3b, v172
	v_exp_f32_e32 v163, v169
	s_waitcnt lgkmcnt(6)
	v_mfma_f32_32x32x16_bf16 v[16:31], v[186:189], v[64:67], v[16:31]
	ds_read_b64_tr_b16 v[186:187], v177 offset:40064
	ds_read_b64_tr_b16 v[188:189], v177 offset:42624
	v_fmamk_f32 v169, v76, 0x3fb8aa3b, v172
	v_exp_f32_e32 v164, v169
	v_fmamk_f32 v169, v77, 0x3fb8aa3b, v172
	v_exp_f32_e32 v165, v169
	s_waitcnt lgkmcnt(6)
	v_mfma_f32_32x32x16_bf16 v[0:15], v[198:201], v[64:67], v[0:15]
	ds_read_b64_tr_b16 v[198:199], v177 offset:40128
	ds_read_b64_tr_b16 v[200:201], v177 offset:42688
	v_fmamk_f32 v169, v78, 0x3fb8aa3b, v172
	v_exp_f32_e32 v166, v169
	v_fmamk_f32 v169, v79, 0x3fb8aa3b, v172
	v_exp_f32_e32 v167, v169
	v_cvt_pk_bf16_f32 v72, v160, v161
	v_cvt_pk_bf16_f32 v73, v162, v163
	v_cvt_pk_bf16_f32 v74, v164, v165
	v_cvt_pk_bf16_f32 v75, v166, v167
	s_nop 1
	s_waitcnt lgkmcnt(6)
	v_mfma_f32_32x32x16_bf16 v[48:63], v[178:181], v[72:75], v[48:63]
	ds_read_b64_tr_b16 v[178:179], v177 offset:45056
	ds_read_b64_tr_b16 v[180:181], v177 offset:47616
	v_add_f32_e32 v190, v190, v160
	v_add_f32_e32 v191, v191, v161
	v_add_f32_e32 v190, v190, v162
	v_add_f32_e32 v191, v191, v163
	v_add_f32_e32 v190, v190, v164
	v_add_f32_e32 v191, v191, v165
	v_add_f32_e32 v190, v190, v166
	v_add_f32_e32 v191, v191, v167
	v_fmamk_f32 v169, v80, 0x3fb8aa3b, v172
	v_exp_f32_e32 v160, v169
	v_fmamk_f32 v169, v81, 0x3fb8aa3b, v172
	v_exp_f32_e32 v161, v169
	s_waitcnt lgkmcnt(6)
	v_mfma_f32_32x32x16_bf16 v[32:47], v[182:185], v[72:75], v[32:47]
	ds_read_b64_tr_b16 v[182:183], v177 offset:45120
	ds_read_b64_tr_b16 v[184:185], v177 offset:47680
	v_fmamk_f32 v169, v82, 0x3fb8aa3b, v172
	v_exp_f32_e32 v162, v169
	v_fmamk_f32 v169, v83, 0x3fb8aa3b, v172
	v_exp_f32_e32 v163, v169
	s_waitcnt lgkmcnt(6)
	v_mfma_f32_32x32x16_bf16 v[16:31], v[186:189], v[72:75], v[16:31]
	ds_read_b64_tr_b16 v[186:187], v177 offset:45184
	ds_read_b64_tr_b16 v[188:189], v177 offset:47744
	v_fmamk_f32 v169, v84, 0x3fb8aa3b, v172
	v_exp_f32_e32 v164, v169
	v_fmamk_f32 v169, v85, 0x3fb8aa3b, v172
	v_exp_f32_e32 v165, v169
	s_waitcnt lgkmcnt(6)
	v_mfma_f32_32x32x16_bf16 v[0:15], v[198:201], v[72:75], v[0:15]
	ds_read_b64_tr_b16 v[198:199], v177 offset:45248
	ds_read_b64_tr_b16 v[200:201], v177 offset:47808
	v_fmamk_f32 v169, v86, 0x3fb8aa3b, v172
	v_exp_f32_e32 v166, v169
	v_fmamk_f32 v169, v87, 0x3fb8aa3b, v172
	v_exp_f32_e32 v167, v169
	v_cvt_pk_bf16_f32 v80, v160, v161
	v_cvt_pk_bf16_f32 v81, v162, v163
	v_cvt_pk_bf16_f32 v82, v164, v165
	v_cvt_pk_bf16_f32 v83, v166, v167
	s_nop 1
	s_waitcnt lgkmcnt(6)
	v_mfma_f32_32x32x16_bf16 v[48:63], v[178:181], v[80:83], v[48:63]
	ds_read_b64_tr_b16 v[178:179], v177 offset:50176
	ds_read_b64_tr_b16 v[180:181], v177 offset:52736
	v_add_f32_e32 v190, v190, v160
	v_add_f32_e32 v191, v191, v161
	v_add_f32_e32 v190, v190, v162
	v_add_f32_e32 v191, v191, v163
	v_add_f32_e32 v190, v190, v164
	v_add_f32_e32 v191, v191, v165
	v_add_f32_e32 v190, v190, v166
	v_add_f32_e32 v191, v191, v167
	v_fmamk_f32 v169, v88, 0x3fb8aa3b, v172
	v_exp_f32_e32 v160, v169
	v_fmamk_f32 v169, v89, 0x3fb8aa3b, v172
	v_exp_f32_e32 v161, v169
	s_waitcnt lgkmcnt(6)
	v_mfma_f32_32x32x16_bf16 v[32:47], v[182:185], v[80:83], v[32:47]
	ds_read_b64_tr_b16 v[182:183], v177 offset:50240
	ds_read_b64_tr_b16 v[184:185], v177 offset:52800
	v_fmamk_f32 v169, v90, 0x3fb8aa3b, v172
	v_exp_f32_e32 v162, v169
	v_fmamk_f32 v169, v91, 0x3fb8aa3b, v172
	v_exp_f32_e32 v163, v169
	s_waitcnt lgkmcnt(6)
	v_mfma_f32_32x32x16_bf16 v[16:31], v[186:189], v[80:83], v[16:31]
	ds_read_b64_tr_b16 v[186:187], v177 offset:50304
	ds_read_b64_tr_b16 v[188:189], v177 offset:52864
	v_fmamk_f32 v169, v92, 0x3fb8aa3b, v172
	v_exp_f32_e32 v164, v169
	v_fmamk_f32 v169, v93, 0x3fb8aa3b, v172
	v_exp_f32_e32 v165, v169
	s_waitcnt lgkmcnt(6)
	v_mfma_f32_32x32x16_bf16 v[0:15], v[198:201], v[80:83], v[0:15]
	ds_read_b64_tr_b16 v[198:199], v177 offset:50368
	ds_read_b64_tr_b16 v[200:201], v177 offset:52928
	v_fmamk_f32 v169, v94, 0x3fb8aa3b, v172
	v_exp_f32_e32 v166, v169
	v_fmamk_f32 v169, v95, 0x3fb8aa3b, v172
	v_exp_f32_e32 v167, v169
	v_cvt_pk_bf16_f32 v88, v160, v161
	v_cvt_pk_bf16_f32 v89, v162, v163
	v_cvt_pk_bf16_f32 v90, v164, v165
	v_cvt_pk_bf16_f32 v91, v166, v167
	s_nop 1
	s_waitcnt lgkmcnt(6)
	v_mfma_f32_32x32x16_bf16 v[48:63], v[178:181], v[88:91], v[48:63]
	v_add_f32_e32 v190, v190, v160
	v_add_f32_e32 v191, v191, v161
	v_add_f32_e32 v190, v190, v162
	v_add_f32_e32 v191, v191, v163
	v_add_f32_e32 v190, v190, v164
	v_add_f32_e32 v191, v191, v165
	v_add_f32_e32 v190, v190, v166
	v_add_f32_e32 v191, v191, v167
	s_waitcnt lgkmcnt(4)
	v_mfma_f32_32x32x16_bf16 v[32:47], v[182:185], v[88:91], v[32:47]
	s_waitcnt lgkmcnt(2)
	v_mfma_f32_32x32x16_bf16 v[16:31], v[186:189], v[88:91], v[16:31]
	s_waitcnt lgkmcnt(0)
	v_mfma_f32_32x32x16_bf16 v[0:15], v[198:201], v[88:91], v[0:15]
	v_add_f32_e32 v176, v190, v191
	v_mov_b32_e32 v80, v174
	s_branch .Lattn2_tail
